# v33 + LDS fragment ds_reads issued before the LDS-DMA block in ffn_in and gemm_res K=2816 k-loops
# baseline (speedup 1.0000x reference)
; DEVI f32x4 mfma16(bf16x8 a, bf16x8 b, f32x4 c) { return __builtin_amdgcn_mfma_f32_16x16x32_bf16(a, b, c, 0, 0, 0); }
;     ...
;     auto issue = [&](int kt, int st) {
;         glds_tile8(va, vb, a0p + (size_t)kt * kstepA, Btile + (size_t)kt * 64, __builtin_amdgcn_readfirstlane(lds0 + st * 32768));
;     };
;     const int sw0 = (quad ^ (l16 >> 1)) * 16;
;     const int aoffb = (wr * 64 + l16) * 128, boffb = 16384 + (wc * 64 + l16) * 128;
;     if (!first_issued) issue(0, 0);
; #pragma unroll 1
;     for (int kt = 0; kt < nk; ++kt) {
;         asm volatile("s_waitcnt vmcnt(0)\n\ts_barrier" ::: "memory");
;         if (kt + 1 < nk) issue(kt + 1, (kt + 1) & 1);
;         const unsigned char* cs = sbase + (kt & 1) * 32768;
;         bf16x8 af0[4], bf0[4], af1[4], bf1[4];
; #pragma unroll
;         for (int i = 0; i < 4; ++i) { af0[i] = *(const bf16x8*)(cs + aoffb + i * 2048 + sw0); bf0[i] = *(const bf16x8*)(cs + boffb + i * 2048 + sw0); }
; #pragma unroll
;         for (int i = 0; i < 4; ++i) { af1[i] = *(const bf16x8*)(cs + aoffb + i * 2048 + (sw0 ^ 64)); bf1[i] = *(const bf16x8*)(cs + boffb + i * 2048 + (sw0 ^ 64)); }
;         __builtin_amdgcn_sched_barrier(0);
; #pragma unroll
;         for (int i = 0; i < 4; ++i)
; #pragma unroll
;             for (int j = 0; j < 4; ++j) acc[i][j] = SWAP ? mfma16(bf0[j], af0[i], acc[i][j]) : mfma16(af0[i], bf0[j], acc[i][j]);
;         __builtin_amdgcn_sched_barrier(0);
; #pragma unroll
;         for (int i = 0; i < 4; ++i)
; #pragma unroll
;             for (int j = 0; j < 4; ++j) acc[i][j] = SWAP ? mfma16(bf1[j], af1[i], acc[i][j]) : mfma16(af1[i], bf1[j], acc[i][j]);
.LBB0_757:
	s_and_b32 s40, s65, 0x8000
	v_add_u32_e32 v77, s40, v74
	v_or_b32_e32 v110, s40, v75
	v_add_u32_e32 v98, v77, v73
	v_add_u32_e32 v106, v110, v73
	v_add_u32_e32 v77, v77, v76
	ds_read_b128 v[78:81], v98
	ds_read_b128 v[82:85], v98 offset:2048
	ds_read_b128 v[86:89], v106 offset:16384
	ds_read_b128 v[90:93], v106 offset:18432
	ds_read_b128 v[94:97], v98 offset:4096
	ds_read_b128 v[98:101], v98 offset:6144
	ds_read_b128 v[102:105], v106 offset:20480
	ds_read_b128 v[106:109], v106 offset:22528
	v_add_u32_e32 v130, v110, v76
	ds_read_b128 v[110:113], v77
	ds_read_b128 v[114:117], v77 offset:2048
	ds_read_b128 v[118:121], v130 offset:16384
	ds_read_b128 v[122:125], v130 offset:18432
	ds_read_b128 v[126:129], v77 offset:4096
	ds_read_b128 v[138:141], v77 offset:6144
	ds_read_b128 v[158:161], v130 offset:20480
	ds_read_b128 v[162:165], v130 offset:22528
	s_cmp_lt_u32 s64, 43
	s_cbranch_scc0 .Lgr_nog
	s_and_b32 s40, s66, 0x8000
	s_add_i32 s40, s47, s40
	s_mov_b32 s41, m0
	s_mov_b32 m0, s40
	s_nop 0
	global_load_lds_dwordx4 v0, s[38:39]
	s_add_u32 m0, m0, 0x1000
	s_nop 0
	global_load_lds_dwordx4 v70, s[38:39]
	s_add_u32 m0, m0, 0x1000
	s_nop 0
	global_load_lds_dwordx4 v71, s[38:39]
	s_add_u32 m0, m0, 0x1000
	s_nop 0
	global_load_lds_dwordx4 v72, s[38:39]
	s_add_u32 m0, m0, 0x1000
	s_nop 0
	global_load_lds_dwordx4 v0, s[34:35]
	s_add_u32 m0, m0, 0x1000
	s_nop 0
	global_load_lds_dwordx4 v70, s[34:35]
	s_add_u32 m0, m0, 0x1000
	s_nop 0
	global_load_lds_dwordx4 v71, s[34:35]
	s_add_u32 m0, m0, 0x1000
	s_nop 0
	global_load_lds_dwordx4 v72, s[34:35]
	s_mov_b32 m0, s41
.Lgr_nog:
	s_add_i32 s64, s64, 1
	s_waitcnt lgkmcnt(13)
	v_mfma_f32_16x16x32_bf16 v[62:65], v[86:89], v[78:81], v[62:65]
	s_waitcnt lgkmcnt(12)
	v_mfma_f32_16x16x32_bf16 v[58:61], v[90:93], v[78:81], v[58:61]
	s_waitcnt lgkmcnt(9)
	v_mfma_f32_16x16x32_bf16 v[54:57], v[102:105], v[78:81], v[54:57]
	s_waitcnt lgkmcnt(8)
	v_mfma_f32_16x16x32_bf16 v[50:53], v[106:109], v[78:81], v[50:53]
	v_mfma_f32_16x16x32_bf16 v[46:49], v[86:89], v[82:85], v[46:49]
	v_mfma_f32_16x16x32_bf16 v[42:45], v[90:93], v[82:85], v[42:45]
	v_mfma_f32_16x16x32_bf16 v[38:41], v[102:105], v[82:85], v[38:41]
	v_mfma_f32_16x16x32_bf16 v[34:37], v[106:109], v[82:85], v[34:37]
	v_mfma_f32_16x16x32_bf16 v[30:33], v[86:89], v[94:97], v[30:33]
	v_mfma_f32_16x16x32_bf16 v[26:29], v[90:93], v[94:97], v[26:29]
	v_mfma_f32_16x16x32_bf16 v[22:25], v[102:105], v[94:97], v[22:25]
	v_mfma_f32_16x16x32_bf16 v[18:21], v[106:109], v[94:97], v[18:21]
	v_mfma_f32_16x16x32_bf16 v[14:17], v[86:89], v[98:101], v[14:17]
	v_mfma_f32_16x16x32_bf16 v[6:9], v[90:93], v[98:101], v[6:9]
	v_mfma_f32_16x16x32_bf16 v[10:13], v[102:105], v[98:101], v[10:13]
	v_mfma_f32_16x16x32_bf16 v[2:5], v[106:109], v[98:101], v[2:5]
	s_add_u32 s34, s34, 0x80
	s_waitcnt lgkmcnt(5)
	v_mfma_f32_16x16x32_bf16 v[62:65], v[118:121], v[110:113], v[62:65]
	s_addc_u32 s35, s35, 0
	s_add_u32 s38, s38, 0x80
	s_addc_u32 s39, s39, 0
	s_waitcnt lgkmcnt(4)
	v_mfma_f32_16x16x32_bf16 v[58:61], v[122:125], v[110:113], v[58:61]
	s_cmp_lg_u32 s64, 44
	s_mov_b32 s65, s66
	s_waitcnt lgkmcnt(1)
	v_mfma_f32_16x16x32_bf16 v[54:57], v[158:161], v[110:113], v[54:57]
	s_waitcnt lgkmcnt(0)
	v_mfma_f32_16x16x32_bf16 v[50:53], v[162:165], v[110:113], v[50:53]
	v_mfma_f32_16x16x32_bf16 v[46:49], v[118:121], v[114:117], v[46:49]
	v_mfma_f32_16x16x32_bf16 v[42:45], v[122:125], v[114:117], v[42:45]
	v_mfma_f32_16x16x32_bf16 v[38:41], v[158:161], v[114:117], v[38:41]
	v_mfma_f32_16x16x32_bf16 v[34:37], v[162:165], v[114:117], v[34:37]
	v_mfma_f32_16x16x32_bf16 v[30:33], v[118:121], v[126:129], v[30:33]
	v_mfma_f32_16x16x32_bf16 v[26:29], v[122:125], v[126:129], v[26:29]
	v_mfma_f32_16x16x32_bf16 v[22:25], v[158:161], v[126:129], v[22:25]
	v_mfma_f32_16x16x32_bf16 v[18:21], v[162:165], v[126:129], v[18:21]
	v_mfma_f32_16x16x32_bf16 v[14:17], v[118:121], v[138:141], v[14:17]
	v_mfma_f32_16x16x32_bf16 v[6:9], v[122:125], v[138:141], v[6:9]
	v_mfma_f32_16x16x32_bf16 v[10:13], v[158:161], v[138:141], v[10:13]
	v_mfma_f32_16x16x32_bf16 v[2:5], v[162:165], v[138:141], v[2:5]
	s_cbranch_scc0 .LBB0_762
.LBB0_758:
	s_add_i32 s66, s65, 0x8000
	s_waitcnt vmcnt(0)
	s_barrier
	s_branch .LBB0_757

; DEVI f32x4 mfma16(bf16x8 a, bf16x8 b, f32x4 c) { return __builtin_amdgcn_mfma_f32_16x16x32_bf16(a, b, c, 0, 0, 0); }
;     ...
;     auto issue = [&](int kt, int st) {
;         glds_tile8(va, vb, a0p + (size_t)kt * kstepA, Btile + (size_t)kt * 64, __builtin_amdgcn_readfirstlane(lds0 + st * 32768));
;     };
;     const int sw0 = (quad ^ (l16 >> 1)) * 16;
;     const int aoffb = (wr * 64 + l16) * 128, boffb = 16384 + (wc * 64 + l16) * 128;
;     if (!first_issued) issue(0, 0);
; #pragma unroll 1
;     for (int kt = 0; kt < nk; ++kt) {
;         asm volatile("s_waitcnt vmcnt(0)\n\ts_barrier" ::: "memory");
;         if (kt + 1 < nk) issue(kt + 1, (kt + 1) & 1);
;         const unsigned char* cs = sbase + (kt & 1) * 32768;
;         bf16x8 af0[4], bf0[4], af1[4], bf1[4];
; #pragma unroll
;         for (int i = 0; i < 4; ++i) { af0[i] = *(const bf16x8*)(cs + aoffb + i * 2048 + sw0); bf0[i] = *(const bf16x8*)(cs + boffb + i * 2048 + sw0); }
; #pragma unroll
;         for (int i = 0; i < 4; ++i) { af1[i] = *(const bf16x8*)(cs + aoffb + i * 2048 + (sw0 ^ 64)); bf1[i] = *(const bf16x8*)(cs + boffb + i * 2048 + (sw0 ^ 64)); }
;         __builtin_amdgcn_sched_barrier(0);
; #pragma unroll
;         for (int i = 0; i < 4; ++i)
; #pragma unroll
;             for (int j = 0; j < 4; ++j) acc[i][j] = SWAP ? mfma16(bf0[j], af0[i], acc[i][j]) : mfma16(af0[i], bf0[j], acc[i][j]);
;         __builtin_amdgcn_sched_barrier(0);
; #pragma unroll
;         for (int i = 0; i < 4; ++i)
; #pragma unroll
;             for (int j = 0; j < 4; ++j) acc[i][j] = SWAP ? mfma16(bf1[j], af1[i], acc[i][j]) : mfma16(af1[i], bf1[j], acc[i][j]);
.LBB0_788:
	s_and_b32 s24, s31, 0x8000
	v_add_u32_e32 v108, s24, v73
	v_or_b32_e32 v109, s24, v74
	v_add_u32_e32 v96, v108, v72
	v_add_u32_e32 v104, v109, v72
	v_add_u32_e32 v128, v108, v75
	ds_read_b128 v[76:79], v96
	ds_read_b128 v[80:83], v96 offset:2048
	ds_read_b128 v[84:87], v104 offset:16384
	ds_read_b128 v[88:91], v104 offset:18432
	ds_read_b128 v[92:95], v96 offset:4096
	ds_read_b128 v[96:99], v96 offset:6144
	ds_read_b128 v[100:103], v104 offset:20480
	ds_read_b128 v[104:107], v104 offset:22528
	v_add_u32_e32 v132, v109, v75
	ds_read_b128 v[108:111], v128
	ds_read_b128 v[112:115], v128 offset:2048
	ds_read_b128 v[116:119], v132 offset:16384
	ds_read_b128 v[120:123], v132 offset:18432
	ds_read_b128 v[124:127], v128 offset:4096
	ds_read_b128 v[128:131], v128 offset:6144
	ds_read_b128 v[138:141], v132 offset:20480
	ds_read_b128 v[158:161], v132 offset:22528
	s_cmp_lg_u32 s31, 0x78000
	s_cbranch_scc0 .Lffn_nog
	s_and_b32 s24, s34, 0x8000
	s_add_i32 s24, s27, s24
	s_mov_b32 s25, m0
	s_mov_b32 m0, s24
	s_nop 0
	global_load_lds_dwordx4 v0, s[14:15]
	s_add_u32 m0, m0, 0x1000
	s_nop 0
	global_load_lds_dwordx4 v68, s[14:15]
	s_add_u32 m0, m0, 0x1000
	s_nop 0
	global_load_lds_dwordx4 v69, s[14:15]
	s_add_u32 m0, m0, 0x1000
	s_nop 0
	global_load_lds_dwordx4 v71, s[14:15]
	s_add_u32 m0, m0, 0x1000
	s_nop 0
	global_load_lds_dwordx4 v0, s[10:11]
	s_add_u32 m0, m0, 0x1000
	s_nop 0
	global_load_lds_dwordx4 v68, s[10:11]
	s_add_u32 m0, m0, 0x1000
	s_nop 0
	global_load_lds_dwordx4 v69, s[10:11]
	s_add_u32 m0, m0, 0x1000
	s_nop 0
	global_load_lds_dwordx4 v71, s[10:11]
	s_mov_b32 m0, s25
.Lffn_nog:
	s_waitcnt lgkmcnt(13)
	v_mfma_f32_16x16x32_bf16 v[58:61], v[84:87], v[76:79], v[58:61]
	s_waitcnt lgkmcnt(12)
	v_mfma_f32_16x16x32_bf16 v[62:65], v[88:91], v[76:79], v[62:65]
	s_waitcnt lgkmcnt(9)
	v_mfma_f32_16x16x32_bf16 v[50:53], v[100:103], v[76:79], v[50:53]
	s_waitcnt lgkmcnt(8)
	v_mfma_f32_16x16x32_bf16 v[54:57], v[104:107], v[76:79], v[54:57]
	v_mfma_f32_16x16x32_bf16 v[42:45], v[84:87], v[80:83], v[42:45]
	v_mfma_f32_16x16x32_bf16 v[46:49], v[88:91], v[80:83], v[46:49]
	v_mfma_f32_16x16x32_bf16 v[34:37], v[100:103], v[80:83], v[34:37]
	v_mfma_f32_16x16x32_bf16 v[38:41], v[104:107], v[80:83], v[38:41]
	v_mfma_f32_16x16x32_bf16 v[26:29], v[84:87], v[92:95], v[26:29]
	v_mfma_f32_16x16x32_bf16 v[30:33], v[88:91], v[92:95], v[30:33]
	v_mfma_f32_16x16x32_bf16 v[18:21], v[100:103], v[92:95], v[18:21]
	v_mfma_f32_16x16x32_bf16 v[22:25], v[104:107], v[92:95], v[22:25]
	v_mfma_f32_16x16x32_bf16 v[6:9], v[84:87], v[96:99], v[6:9]
	v_mfma_f32_16x16x32_bf16 v[14:17], v[88:91], v[96:99], v[14:17]
	v_mfma_f32_16x16x32_bf16 v[2:5], v[100:103], v[96:99], v[2:5]
	v_mfma_f32_16x16x32_bf16 v[10:13], v[104:107], v[96:99], v[10:13]
	s_add_u32 s10, s10, 0x80
	s_waitcnt lgkmcnt(5)
	v_mfma_f32_16x16x32_bf16 v[58:61], v[116:119], v[108:111], v[58:61]
	s_addc_u32 s11, s11, 0
	s_add_u32 s14, s14, 0x80
	s_addc_u32 s15, s15, 0
	s_waitcnt lgkmcnt(4)
	v_mfma_f32_16x16x32_bf16 v[62:65], v[120:123], v[108:111], v[62:65]
	s_cmp_lg_u32 s34, 0x80000
	s_mov_b32 s31, s34
	s_waitcnt lgkmcnt(1)
	v_mfma_f32_16x16x32_bf16 v[50:53], v[138:141], v[108:111], v[50:53]
	s_waitcnt lgkmcnt(0)
	v_mfma_f32_16x16x32_bf16 v[54:57], v[158:161], v[108:111], v[54:57]
	v_mfma_f32_16x16x32_bf16 v[42:45], v[116:119], v[112:115], v[42:45]
	v_mfma_f32_16x16x32_bf16 v[46:49], v[120:123], v[112:115], v[46:49]
	v_mfma_f32_16x16x32_bf16 v[34:37], v[138:141], v[112:115], v[34:37]
	v_mfma_f32_16x16x32_bf16 v[38:41], v[158:161], v[112:115], v[38:41]
	v_mfma_f32_16x16x32_bf16 v[26:29], v[116:119], v[124:127], v[26:29]
	v_mfma_f32_16x16x32_bf16 v[30:33], v[120:123], v[124:127], v[30:33]
	v_mfma_f32_16x16x32_bf16 v[18:21], v[138:141], v[124:127], v[18:21]
	v_mfma_f32_16x16x32_bf16 v[22:25], v[158:161], v[124:127], v[22:25]
	v_mfma_f32_16x16x32_bf16 v[6:9], v[116:119], v[128:131], v[6:9]
	v_mfma_f32_16x16x32_bf16 v[14:17], v[120:123], v[128:131], v[14:17]
	v_mfma_f32_16x16x32_bf16 v[2:5], v[138:141], v[128:131], v[2:5]
	v_mfma_f32_16x16x32_bf16 v[10:13], v[158:161], v[128:131], v[10:13]
	s_cbranch_scc0 .LBB0_793
.LBB0_789:
	s_add_i32 s34, s31, 0x8000
	s_cmp_lg_u32 s31, 0
	s_cbranch_scc1 .Lffn_fullw
	s_cmp_eq_u32 s17, 0
	s_cbranch_scc1 .Lffn_fullw
	s_waitcnt vmcnt(8)
	s_branch .Lffn_bar2

;     ...
;     if (!first_issued) issue(0, 0);
; #pragma unroll 1
;     for (int kt = 0; kt < nk; ++kt) {
;         asm volatile("s_waitcnt vmcnt(0)\n\ts_barrier" ::: "memory");
;         if (kt + 1 < nk) issue(kt + 1, (kt + 1) & 1);
.Lffn_bar2:
	s_barrier
	s_branch .LBB0_788
